# banded attention unit heads: store-ack / partial-load vmcnt(0) waits ahead of the tile loads removed (SWA sink load, NA first tile quarter, dilated)
# baseline (speedup 1.0000x reference)
.LBB0_500:
	s_or_b64 exec, exec, s[2:3]
	s_and_b32 s2, s10, 0x3fffffc0
	s_add_i32 s4, s21, s56
	s_lshl_b32 s2, s2, 2
	s_add_i32 s22, s2, 0
	s_ashr_i32 s2, s4, 7
	s_lshl_b32 s3, s21, 8
	s_ashr_i32 s10, s10, 1
	s_bfe_u32 s5, s4, 0x20005
	s_and_b32 s11, s3, 0x1f00
	s_ashr_i32 s3, s2, 31
	s_and_b32 s12, s10, 0xffffffe0
	s_and_b32 s25, s18, 0x1f00
	s_add_i32 s22, s22, 0x1c800
	s_lshl_b64 s[8:9], s[2:3], 13
	s_add_i32 s24, s12, s11
	s_lshl_b32 s23, s5, 6
	s_lshl_b32 s40, s5, 7
	s_lshl_b32 s2, s5, 2
	v_and_b32_e32 v120, 31, v2
	s_add_u32 s2, s16, s2
	v_or_b32_e32 v0, s24, v120
	s_addc_u32 s3, s17, 0
	v_ashrrev_i32_e32 v1, 31, v0
	v_mov_b64_e32 v[4:5], s[2:3]
	s_add_i32 s2, s11, 0xffffff80
	v_ashrrev_i32_e32 v10, 3, v2
	v_lshl_add_u64 v[0:1], s[8:9], 0, v[0:1]
	global_load_dword v3, v[4:5], off
	v_add_u32_e32 v4, s2, v10
	v_mov_b32_e32 v14, 0x1fff
	v_lshlrev_b64 v[0:1], 13, v[0:1]
	v_med3_i32 v4, v4, 0, v14
	v_lshl_add_u64 v[0:1], s[74:75], 0, v[0:1]
	v_or_b32_e32 v4, s8, v4
	v_mov_b32_e32 v5, s9
	s_and_b32 s2, s4, 64
	v_lshl_add_u64 v[0:1], v[0:1], 0, s[40:41]
	v_lshlrev_b64 v[6:7], 13, v[4:5]
	s_lshl_b32 s40, s2, 1
	v_lshlrev_b32_e32 v4, 4, v2
	s_sub_i32 s2, s11, 64
	v_lshl_add_u64 v[6:7], s[74:75], 0, v[6:7]
	v_and_b32_e32 v8, 0x70, v4
	v_add_u32_e32 v4, s2, v10
	v_lshl_add_u64 v[6:7], v[6:7], 0, s[40:41]
	v_mov_b32_e32 v9, v233
	v_med3_i32 v4, v4, 0, v14
	v_lshl_add_u64 v[6:7], v[6:7], 0, v[8:9]
	v_or_b32_e32 v4, s8, v4
	global_load_dwordx4 v[64:67], v[6:7], off offset:1344
	global_load_dwordx4 v[68:71], v[6:7], off offset:1600
	v_lshlrev_b64 v[6:7], 13, v[4:5]
	v_lshl_add_u64 v[6:7], s[74:75], 0, v[6:7]
	v_add_u32_e32 v12, s11, v10
	v_lshl_add_u64 v[6:7], v[6:7], 0, s[40:41]
	v_med3_i32 v4, v12, 0, v14
	v_lshl_add_u64 v[6:7], v[6:7], 0, v[8:9]
	v_or_b32_e32 v4, s8, v4
	global_load_dwordx4 v[72:75], v[6:7], off offset:1344
	global_load_dwordx4 v[76:79], v[6:7], off offset:1600
	v_lshlrev_b64 v[6:7], 13, v[4:5]
	v_lshl_add_u64 v[6:7], s[74:75], 0, v[6:7]
	v_add_u32_e32 v4, 64, v12
	v_lshl_add_u64 v[6:7], v[6:7], 0, s[40:41]
	v_med3_i32 v4, v4, 0, v14
	v_lshl_add_u64 v[6:7], v[6:7], 0, v[8:9]
	v_or_b32_e32 v4, s8, v4
	global_load_dwordx4 v[80:83], v[6:7], off offset:1344
	global_load_dwordx4 v[84:87], v[6:7], off offset:1600
	v_lshlrev_b64 v[6:7], 13, v[4:5]
	v_lshl_add_u64 v[6:7], s[74:75], 0, v[6:7]
	v_bfe_u32 v4, v2, 5, 1
	v_lshl_add_u64 v[6:7], v[6:7], 0, s[40:41]
	v_lshlrev_b32_e32 v232, 4, v4
	v_lshl_add_u64 v[6:7], v[6:7], 0, v[8:9]
	v_lshl_add_u64 v[0:1], v[0:1], 0, v[232:233]
	global_load_dwordx4 v[88:91], v[6:7], off offset:1344
	global_load_dwordx4 v[92:95], v[6:7], off offset:1600
	global_load_dwordx4 v[96:99], v[0:1], off offset:832
	global_load_dwordx4 v[100:103], v[0:1], off offset:864
	global_load_dwordx4 v[104:107], v[0:1], off offset:896
	global_load_dwordx4 v[108:111], v[0:1], off offset:928
	v_lshrrev_b32_e32 v0, 2, v2
	v_lshlrev_b32_e32 v121, 2, v4
	v_and_or_b32 v13, v0, 3, v121
	v_add_u32_e32 v0, 0x80, v12
	v_med3_i32 v0, v0, 0, v14
	v_cmp_eq_u32_e64 s[2:3], 0, v4
	v_or_b32_e32 v4, s8, v0
	s_movk_i32 s11, 0x90
	v_lshlrev_b64 v[0:1], 13, v[4:5]
	v_add_u32_e32 v4, 0xc0, v12
	v_mul_lo_u32 v6, v10, s11
	v_med3_i32 v4, v4, 0, v14
	v_add_u32_e32 v6, 0, v6
	v_or_b32_e32 v4, s8, v4
	v_add_u32_e32 v123, v6, v8
	v_lshlrev_b64 v[6:7], 13, v[4:5]
	v_add_u32_e32 v4, 0x100, v12
	v_med3_i32 v4, v4, 0, v14
	v_lshl_add_u64 v[0:1], s[74:75], 0, v[0:1]
	v_or_b32_e32 v4, s8, v4
	v_lshl_add_u64 v[0:1], v[0:1], 0, s[40:41]
	v_lshlrev_b64 v[10:11], 13, v[4:5]
	v_add_u32_e32 v4, 0x140, v12
	v_lshl_add_u64 v[112:113], v[0:1], 0, v[8:9]
	v_lshl_add_u64 v[0:1], s[74:75], 0, v[6:7]
	v_med3_i32 v4, v4, 0, v14
	v_lshl_add_u64 v[0:1], v[0:1], 0, s[40:41]
	v_or_b32_e32 v4, s8, v4
	v_lshl_add_u64 v[114:115], v[0:1], 0, v[8:9]
	v_lshl_add_u64 v[0:1], s[74:75], 0, v[10:11]
	v_lshlrev_b64 v[4:5], 13, v[4:5]
	v_lshl_add_u64 v[0:1], v[0:1], 0, s[40:41]
	v_lshl_add_u64 v[116:117], v[0:1], 0, v[8:9]
	v_lshl_add_u64 v[0:1], s[74:75], 0, v[4:5]
	s_waitcnt vmcnt(0) lgkmcnt(0)
	v_mul_f32_e32 v136, 0x3fb8aa3b, v3
	v_lshlrev_b32_e32 v3, 2, v120
	v_lshl_add_u64 v[0:1], v[0:1], 0, s[40:41]
	s_lshl_b32 s5, s10, 2
	v_lshl_add_u64 v[118:119], v[0:1], 0, v[8:9]
	v_sub_u32_e32 v0, v232, v3
	s_and_b32 s5, s5, 0xffffff80
	v_subrev_u32_e32 v125, s5, v0
	v_sub_u32_e32 v0, v121, v120
	v_subrev_u32_e32 v126, s12, v0
	v_lshlrev_b32_e32 v0, 1, v2
	v_and_b32_e32 v1, 3, v2
	v_mul_u32_u24_e32 v12, 0x90, v13
	v_and_b32_e32 v0, 32, v0
	v_lshlrev_b32_e32 v1, 3, v1
	v_mov_b32_e32 v14, v233
	v_mov_b32_e32 v15, v233
	s_max_i32 s26, s24, 0x80
	s_min_i32 s27, s24, 0x1f60
	v_add_u32_e32 v122, s22, v3
	v_add3_u32 v128, v12, v0, v1
	v_mov_b32_e32 v0, v233
	v_mov_b32_e32 v1, v233
	v_mov_b32_e32 v2, v233
	v_mov_b32_e32 v3, v233
	v_mov_b32_e32 v4, v233
	v_mov_b32_e32 v5, v233
	v_mov_b32_e32 v6, v233
	v_mov_b32_e32 v7, v233
	v_mov_b32_e32 v8, v233
	v_mov_b32_e32 v10, v233
	v_mov_b32_e32 v11, v233
	v_mov_b32_e32 v12, v233
	v_mov_b32_e32 v13, v233
	v_mov_b64_e32 v[30:31], v[14:15]
	s_mov_b32 s4, 0
	v_cndmask_b32_e64 v124, 0, 1.0, s[2:3]
	s_addk_i32 s26, 0xff80
	s_addk_i32 s27, 0x9f
	s_sub_i32 s28, 0, s12
	v_or_b32_e32 v127, s25, v121
	v_mad_u32_u24 v129, v120, s11, v232
	s_mov_b64 s[10:11], -1
	v_mov_b64_e32 v[28:29], v[12:13]
	v_mov_b64_e32 v[26:27], v[10:11]
	v_mov_b64_e32 v[24:25], v[8:9]
	v_mov_b64_e32 v[22:23], v[6:7]
	v_mov_b64_e32 v[20:21], v[4:5]
	v_mov_b64_e32 v[18:19], v[2:3]
	v_mov_b64_e32 v[16:17], v[0:1]
	ds_write_b128 v123, v[64:67]
	ds_write_b128 v123, v[68:71] offset:36864
	ds_write_b128 v123, v[72:75] offset:9216
	ds_write_b128 v123, v[76:79] offset:46080
	ds_write_b128 v123, v[80:83] offset:18432
	ds_write_b128 v123, v[84:87] offset:55296
	ds_write_b128 v123, v[88:91] offset:27648
	ds_write_b128 v123, v[92:95] offset:64512
	s_waitcnt lgkmcnt(0)
	s_barrier
	s_branch .LBB0_502

.LBB0_603:
	s_or_b64 exec, exec, s[2:3]
	s_add_i32 s2, s77, s56
	s_bfe_u32 s4, s2, 0x20005
	s_ashr_i32 s2, s2, 7
	s_ashr_i32 s3, s2, 31
	s_lshl_b64 s[78:79], s[2:3], 13
	s_lshl_b32 s2, s77, 2
	s_and_b32 s2, s2, 0x7c
	v_sub_u32_e64 v0, s2, 4 clamp
	v_ashrrev_i32_e32 v3, 3, v2
	v_lshl_add_u32 v14, v0, 6, v3
	v_min_i32_e32 v0, 0x1fff, v14
	v_ashrrev_i32_e32 v1, 31, v0
	v_lshl_add_u64 v[0:1], s[78:79], 0, v[0:1]
	v_readlane_b32 s40, v254, 32
	v_lshlrev_b64 v[0:1], 13, v[0:1]
	v_readlane_b32 s41, v254, 33
	s_lshl_b32 s40, s4, 7
	v_lshl_add_u64 v[0:1], s[74:75], 0, v[0:1]
	v_lshl_add_u64 v[4:5], v[0:1], 0, s[40:41]
	v_lshlrev_b32_e32 v0, 4, v2
	v_and_b32_e32 v0, 0x70, v0
	v_mov_b32_e32 v1, v233
	v_lshl_add_u64 v[4:5], v[4:5], 0, v[0:1]
	global_load_dwordx4 v[48:51], v[4:5], off offset:2368
	global_load_dwordx4 v[52:55], v[4:5], off offset:2880
	v_min_i32_e32 v4, 0x1fbf, v14
	v_add_u32_e32 v4, 64, v4
	v_ashrrev_i32_e32 v5, 31, v4
	v_lshl_add_u64 v[4:5], s[78:79], 0, v[4:5]
	v_lshlrev_b64 v[4:5], 13, v[4:5]
	v_lshl_add_u64 v[4:5], s[74:75], 0, v[4:5]
	v_lshl_add_u64 v[4:5], v[4:5], 0, s[40:41]
	v_lshl_add_u64 v[4:5], v[4:5], 0, v[0:1]
	global_load_dwordx4 v[56:59], v[4:5], off offset:2368
	global_load_dwordx4 v[60:63], v[4:5], off offset:2880
	v_min_i32_e32 v4, 0x1f7f, v14
	v_add_u32_e32 v4, 0x80, v4
	v_ashrrev_i32_e32 v5, 31, v4
	v_lshl_add_u64 v[4:5], s[78:79], 0, v[4:5]
	v_lshlrev_b64 v[4:5], 13, v[4:5]
	v_lshl_add_u64 v[4:5], s[74:75], 0, v[4:5]
	v_lshl_add_u64 v[4:5], v[4:5], 0, s[40:41]
	v_lshl_add_u64 v[4:5], v[4:5], 0, v[0:1]
	global_load_dwordx4 v[64:67], v[4:5], off offset:2368
	global_load_dwordx4 v[68:71], v[4:5], off offset:2880
	v_min_i32_e32 v4, 0x1f3f, v14
	v_add_u32_e32 v4, 0xc0, v4
	v_ashrrev_i32_e32 v5, 31, v4
	v_lshl_add_u64 v[4:5], s[78:79], 0, v[4:5]
	v_lshlrev_b64 v[4:5], 13, v[4:5]
	v_lshl_add_u64 v[4:5], s[74:75], 0, v[4:5]
	v_lshl_add_u64 v[4:5], v[4:5], 0, s[40:41]
	v_lshl_add_u64 v[4:5], v[4:5], 0, v[0:1]
	global_load_dwordx4 v[72:75], v[4:5], off offset:2368
	global_load_dwordx4 v[76:79], v[4:5], off offset:2880
	v_min_i32_e32 v4, 0x1eff, v14
	v_add_u32_e32 v4, 0x100, v4
	v_ashrrev_i32_e32 v5, 31, v4
	v_lshl_add_u64 v[4:5], s[78:79], 0, v[4:5]
	v_lshlrev_b64 v[4:5], 13, v[4:5]
	v_lshl_add_u64 v[4:5], s[74:75], 0, v[4:5]
	v_lshl_add_u64 v[4:5], v[4:5], 0, s[40:41]
	v_lshl_add_u64 v[4:5], v[4:5], 0, v[0:1]
	s_bfe_u32 s3, s8, 0x50002
	global_load_dwordx4 v[80:83], v[4:5], off offset:2368
	global_load_dwordx4 v[84:87], v[4:5], off offset:2880
	v_min_i32_e32 v4, 0x1ebf, v14
	s_lshl_b32 s63, s3, 8
	s_lshl_b32 s3, s3, 2
	v_add_u32_e32 v4, 0x140, v4
	s_min_u32 s3, s3, 4
	v_ashrrev_i32_e32 v5, 31, v4
	s_lshl_b32 s62, s3, 6
	s_and_b32 s3, s6, 0x3fffffc0
	v_lshl_add_u64 v[4:5], s[78:79], 0, v[4:5]
	s_lshl_b32 s3, s3, 2
	v_lshlrev_b64 v[4:5], 13, v[4:5]
	s_add_i32 s88, s3, 0
	s_ashr_i32 s3, s6, 7
	v_lshl_add_u64 v[4:5], s[74:75], 0, v[4:5]
	s_and_b32 s3, s3, -2
	v_lshl_add_u64 v[4:5], v[4:5], 0, s[40:41]
	s_add_i32 s3, s3, s2
	s_lshr_b32 s2, s6, 2
	v_lshl_add_u64 v[4:5], v[4:5], 0, v[0:1]
	s_and_b32 s86, s2, 48
	global_load_dwordx4 v[88:91], v[4:5], off offset:2368
	global_load_dwordx4 v[92:95], v[4:5], off offset:2880
	v_sub_u32_e64 v4, s86, 8 clamp
	v_and_b32_e32 v7, 15, v2
	v_readfirstlane_b32 s2, v4
	v_bfe_u32 v4, v2, 4, 1
	v_or_b32_e32 v126, s3, v4
	v_lshlrev_b32_e32 v4, 6, v126
	v_or3_b32 v4, v4, v7, s86
	v_ashrrev_i32_e32 v5, 31, v4
	v_lshl_add_u64 v[4:5], s[78:79], 0, v[4:5]
	v_lshlrev_b64 v[4:5], 13, v[4:5]
	v_bfe_u32 v6, v2, 5, 1
	v_lshl_add_u64 v[4:5], s[74:75], 0, v[4:5]
	v_lshl_add_u64 v[4:5], v[4:5], 0, s[40:41]
	v_lshlrev_b32_e32 v232, 4, v6
	v_lshl_add_u64 v[4:5], v[4:5], 0, v[232:233]
	global_load_dwordx4 v[96:99], v[4:5], off offset:1856
	global_load_dwordx4 v[100:103], v[4:5], off offset:1888
	global_load_dwordx4 v[104:107], v[4:5], off offset:1920
	global_load_dwordx4 v[108:111], v[4:5], off offset:1952
	s_min_u32 s64, s2, 32
	v_lshlrev_b32_e32 v124, 2, v6
	v_or_b32_e32 v16, s86, v7
	v_or_b32_e32 v17, s64, v124
	v_sub_u32_e32 v18, v17, v16
	v_sub_u32_e64 v5, v16, 8 clamp
	v_max_i32_e32 v18, -15, v18
	v_min_u32_e32 v32, 48, v5
	v_add_u32_e32 v18, 15, v18
	v_add_u32_e32 v33, 16, v32
	v_min_u32_e32 v135, 30, v18
	v_or_b32_e32 v18, 1, v17
	v_writelane_b32 v255, s8, 9
	v_cmp_ge_u32_e64 s[8:9], v18, v32
	v_cmp_lt_u32_e64 s[10:11], v18, v33
	v_sub_u32_e32 v18, v18, v16
	v_max_i32_e32 v18, -15, v18
	v_add_u32_e32 v18, 15, v18
	v_min_u32_e32 v136, 30, v18
	v_or_b32_e32 v18, 2, v17
	v_cmp_ge_u32_e64 s[12:13], v18, v32
	v_cmp_lt_u32_e64 s[14:15], v18, v33
	v_sub_u32_e32 v18, v18, v16
	v_max_i32_e32 v18, -15, v18
	v_add_u32_e32 v18, 15, v18
	v_min_u32_e32 v137, 30, v18
	v_or_b32_e32 v18, 3, v17
	v_cmp_ge_u32_e64 s[16:17], v18, v32
	v_cmp_lt_u32_e64 s[18:19], v18, v33
	v_sub_u32_e32 v18, v18, v16
	v_max_i32_e32 v18, -15, v18
	v_add_u32_e32 v18, 15, v18
	v_min_u32_e32 v138, 30, v18
	v_add_u32_e32 v18, 8, v17
	v_cmp_ge_u32_e64 s[20:21], v18, v32
	v_cmp_lt_u32_e64 s[22:23], v18, v33
	v_sub_u32_e32 v18, v18, v16
	v_max_i32_e32 v18, -15, v18
	v_add_u32_e32 v18, 15, v18
	v_min_u32_e32 v139, 30, v18
	v_add_u32_e32 v18, 9, v17
	v_cmp_ge_u32_e64 s[24:25], v18, v32
	v_cmp_lt_u32_e64 s[26:27], v18, v33
	v_sub_u32_e32 v18, v18, v16
	v_max_i32_e32 v18, -15, v18
	v_add_u32_e32 v18, 15, v18
	v_min_u32_e32 v140, 30, v18
	v_add_u32_e32 v18, 10, v17
	v_cmp_ge_u32_e64 s[28:29], v18, v32
	v_cmp_lt_u32_e64 s[30:31], v18, v33
	v_sub_u32_e32 v18, v18, v16
	v_max_i32_e32 v18, -15, v18
	v_add_u32_e32 v18, 15, v18
	v_min_u32_e32 v141, 30, v18
	v_add_u32_e32 v18, 11, v17
	v_cmp_ge_u32_e64 s[34:35], v18, v32
	v_cmp_lt_u32_e64 s[36:37], v18, v33
	v_sub_u32_e32 v18, v18, v16
	v_max_i32_e32 v18, -15, v18
	s_movk_i32 s65, 0x90
	v_add_u32_e32 v18, 15, v18
	s_lshl_b32 s2, s4, 6
	v_mul_lo_u32 v3, v3, s65
	v_min_u32_e32 v142, 30, v18
	v_add_u32_e32 v18, 16, v17
	v_writelane_b32 v255, s2, 10
	v_add_u32_e32 v7, 0, v3
	s_add_i32 s2, 0, 0x12000
	v_cmp_ge_u32_e64 s[38:39], v18, v32
	v_sub_u32_e32 v18, v18, v16
	v_add_u32_e32 v127, v7, v0
	v_add_u32_e32 v7, s2, v3
	v_max_i32_e32 v18, -15, v18
	v_add_u32_e32 v128, v7, v0
	v_add_u32_e32 v7, s89, v3
	v_readlane_b32 s2, v254, 10
	v_add_u32_e32 v18, 15, v18
	v_readlane_b32 s42, v254, 34
	v_readlane_b32 s43, v254, 35
	v_readlane_b32 s44, v254, 36
	v_readlane_b32 s45, v254, 37
	v_add_u32_e32 v129, v7, v0
	v_add_u32_e32 v7, s2, v3
	v_readlane_b32 s2, v254, 11
	v_min_u32_e32 v143, 30, v18
	v_add_u32_e32 v18, 17, v17
	v_max_i32_e32 v4, 4, v126
	v_add_u32_e32 v3, s2, v3
	s_max_i32 s2, s3, 4
	v_cmp_ge_u32_e64 s[42:43], v18, v32
	v_cmp_lt_u32_e64 s[44:45], v18, v33
	v_sub_u32_e32 v18, v18, v16
	v_add_u32_e32 v4, -4, v4
	s_add_i32 s2, s2, -4
	v_max_i32_e32 v18, -15, v18
	v_min_u32_e32 v133, 0x78, v4
	s_min_u32 s89, s2, 0x78
	s_max_i32 s2, s3, 3
	v_min_i32_e32 v4, 0x1e7f, v14
	v_add_u32_e32 v18, 15, v18
	v_readlane_b32 s46, v254, 38
	v_readlane_b32 s47, v254, 39
	v_readlane_b32 s48, v254, 40
	v_readlane_b32 s49, v254, 41
	s_add_i32 s2, s2, -3
	v_add_u32_e32 v4, 0x180, v4
	v_min_u32_e32 v144, 30, v18
	v_add_u32_e32 v18, 18, v17
	v_writelane_b32 v255, s3, 11
	s_min_u32 s72, s2, 0x78
	v_cmp_eq_u32_e64 s[2:3], 0, v6
	v_ashrrev_i32_e32 v5, 31, v4
	v_min_i32_e32 v6, 0x1e3f, v14
	v_cmp_ge_u32_e64 s[46:47], v18, v32
	v_cmp_lt_u32_e64 s[48:49], v18, v33
	v_sub_u32_e32 v18, v18, v16
	v_lshl_add_u64 v[4:5], s[78:79], 0, v[4:5]
	v_add_u32_e32 v6, 0x1c0, v6
	v_max_i32_e32 v18, -15, v18
	v_add_u32_e32 v131, v7, v0
	v_lshlrev_b64 v[4:5], 13, v[4:5]
	v_ashrrev_i32_e32 v7, 31, v6
	v_min_i32_e32 v8, 0x1dff, v14
	s_mov_b64 s[68:69], s[40:41]
	v_add_u32_e32 v18, 15, v18
	v_readlane_b32 s50, v254, 42
	v_readlane_b32 s51, v254, 43
	v_readlane_b32 s52, v254, 44
	v_readlane_b32 s53, v254, 45
	v_and_b32_e32 v125, 31, v2
	s_add_i32 s88, s88, 0x1c800
	v_lshl_add_u64 v[6:7], s[78:79], 0, v[6:7]
	v_add_u32_e32 v8, 0x200, v8
	v_min_u32_e32 v145, 30, v18
	v_add_u32_e32 v18, 19, v17
	v_lshl_add_u64 v[4:5], s[74:75], 0, v[4:5]
	s_mov_b32 s81, s69
	v_readlane_b32 s54, v254, 46
	v_readlane_b32 s55, v254, 47
	v_lshl_add_u32 v130, v125, 2, s88
	v_lshlrev_b64 v[6:7], 13, v[6:7]
	v_ashrrev_i32_e32 v9, 31, v8
	v_min_i32_e32 v10, 0x1dbf, v14
	v_cmp_ge_u32_e64 s[50:51], v18, v32
	v_cmp_lt_u32_e64 s[52:53], v18, v33
	v_sub_u32_e32 v18, v18, v16
	v_lshl_add_u64 v[4:5], v[4:5], 0, s[68:69]
	v_writelane_b32 v254, s80, 32
	v_lshl_add_u64 v[8:9], s[78:79], 0, v[8:9]
	v_add_u32_e32 v10, 0x240, v10
	v_max_i32_e32 v18, -15, v18
	v_lshl_add_u64 v[112:113], v[4:5], 0, v[0:1]
	v_lshl_add_u64 v[4:5], s[74:75], 0, v[6:7]
	v_writelane_b32 v254, s81, 33
	v_lshlrev_b64 v[8:9], 13, v[8:9]
	v_ashrrev_i32_e32 v11, 31, v10
	v_min_i32_e32 v12, 0x1d7f, v14
	v_add_u32_e32 v18, 15, v18
	v_lshl_add_u64 v[4:5], v[4:5], 0, s[68:69]
	v_writelane_b32 v254, s82, 34
	v_lshl_add_u64 v[10:11], s[78:79], 0, v[10:11]
	v_add_u32_e32 v12, 0x280, v12
	v_min_u32_e32 v146, 30, v18
	v_add_u32_e32 v18, 24, v17
	v_lshl_add_u64 v[114:115], v[4:5], 0, v[0:1]
	v_lshl_add_u64 v[4:5], s[74:75], 0, v[8:9]
	v_writelane_b32 v254, s83, 35
	v_lshlrev_b64 v[10:11], 13, v[10:11]
	v_ashrrev_i32_e32 v13, 31, v12
	v_min_i32_e32 v14, 0x1d3f, v14
	v_cmp_ge_u32_e64 s[54:55], v18, v32
	v_cmp_lt_u32_e64 s[56:57], v18, v33
	v_sub_u32_e32 v18, v18, v16
	v_lshl_add_u64 v[4:5], v[4:5], 0, s[68:69]
	v_writelane_b32 v254, s84, 36
	v_add_u32_e32 v132, v3, v0
	v_lshrrev_b32_e32 v3, 2, v2
	v_lshl_add_u64 v[12:13], s[78:79], 0, v[12:13]
	v_add_u32_e32 v14, 0x2c0, v14
	v_max_i32_e32 v18, -15, v18
	v_lshl_add_u64 v[116:117], v[4:5], 0, v[0:1]
	v_lshl_add_u64 v[4:5], s[74:75], 0, v[10:11]
	v_writelane_b32 v254, s85, 37
	v_and_or_b32 v3, v3, 3, v124
	v_lshlrev_b64 v[12:13], 13, v[12:13]
	v_ashrrev_i32_e32 v15, 31, v14
	v_add_u32_e32 v18, 15, v18
	v_lshlrev_b32_e32 v19, 1, v2
	v_lshl_add_u64 v[4:5], v[4:5], 0, s[68:69]
	v_writelane_b32 v254, s86, 38
	v_lshl_add_u64 v[14:15], s[78:79], 0, v[14:15]
	v_min_u32_e32 v147, 30, v18
	v_add_u32_e32 v18, 25, v17
	v_mul_u32_u24_e32 v3, 0x90, v3
	s_mul_i32 s60, s64, 0x90
	v_and_b32_e32 v19, 32, v19
	v_lshl_add_u64 v[118:119], v[4:5], 0, v[0:1]
	v_lshl_add_u64 v[4:5], s[74:75], 0, v[12:13]
	v_writelane_b32 v254, s87, 39
	v_lshlrev_b64 v[14:15], 13, v[14:15]
	v_cmp_ge_u32_e64 s[58:59], v18, v32
	v_add3_u32 v3, v3, s60, v19
	v_mov_b32_e32 v19, s60
	v_cmp_lt_u32_e64 s[60:61], v18, v33
	v_sub_u32_e32 v18, v18, v16
	v_lshl_add_u64 v[4:5], v[4:5], 0, s[68:69]
	v_writelane_b32 v254, s88, 40
	v_max_i32_e32 v18, -15, v18
	v_lshl_add_u64 v[120:121], v[4:5], 0, v[0:1]
	v_lshl_add_u64 v[4:5], s[74:75], 0, v[14:15]
	v_writelane_b32 v254, s89, 41
	v_add_u32_e32 v18, 15, v18
	v_add_u32_e32 v34, 26, v17
	v_add_u32_e32 v35, 27, v17
	v_writelane_b32 v254, s90, 42
	v_lshl_add_u64 v[4:5], v[4:5], 0, s[68:69]
	v_min_u32_e32 v148, 30, v18
	v_sub_u32_e32 v18, v34, v16
	v_sub_u32_e32 v16, v35, v16
	v_writelane_b32 v254, s91, 43
	v_lshl_add_u64 v[122:123], v[4:5], 0, v[0:1]
	v_and_b32_e32 v0, 3, v2
	v_max_i32_e32 v18, -15, v18
	v_max_i32_e32 v16, -15, v16
	v_writelane_b32 v254, s92, 44
	v_lshlrev_b32_e32 v0, 3, v0
	v_add_u32_e32 v18, 15, v18
	v_add_u32_e32 v16, 15, v16
	v_writelane_b32 v254, s93, 45
	v_add3_u32 v151, v3, v0, 0
	v_mad_u32_u24 v0, v125, s65, v19
	v_mov_b32_e32 v14, v233
	v_mov_b32_e32 v15, v233
	v_cmp_ge_u32_e64 s[4:5], v17, v32
	v_cmp_lt_u32_e64 s[6:7], v17, v33
	v_cmp_lt_u32_e64 s[40:41], v17, v32
	s_or_b32 s63, s64, s63
	v_min_u32_e32 v149, 30, v18
	v_min_u32_e32 v150, 30, v16
	v_writelane_b32 v254, s94, 46
	v_add3_u32 v152, v0, v232, 0
	v_mov_b32_e32 v0, v233
	v_mov_b32_e32 v2, v233
	v_mov_b32_e32 v3, v233
	v_mov_b32_e32 v4, v233
	v_mov_b32_e32 v5, v233
	v_mov_b32_e32 v6, v233
	v_mov_b32_e32 v7, v233
	v_mov_b32_e32 v8, v233
	v_mov_b32_e32 v9, v233
	v_mov_b32_e32 v10, v233
	v_mov_b32_e32 v11, v233
	v_mov_b32_e32 v12, v233
	v_mov_b32_e32 v13, v233
	v_mov_b64_e32 v[30:31], v[14:15]
	s_add_i32 s72, s72, 8
	v_add_u32_e32 v134, 8, v133
	s_mov_b32 s70, 0
	s_sub_i32 s73, s63, s62
	v_cmp_ge_u32_e64 s[62:63], v34, v32
	v_writelane_b32 v254, s95, 47
	v_mov_b32_e32 v153, 0
	v_mov_b32_e32 v154, 0xf149f2ca
	v_mov_b64_e32 v[28:29], v[12:13]
	v_mov_b64_e32 v[26:27], v[10:11]
	v_mov_b64_e32 v[24:25], v[8:9]
	v_mov_b64_e32 v[22:23], v[6:7]
	v_mov_b64_e32 v[20:21], v[4:5]
	v_mov_b64_e32 v[18:19], v[2:3]
	v_mov_b64_e32 v[16:17], v[0:1]
	v_cmp_lt_u32_e64 s[64:65], v34, v33
	v_cmp_ge_u32_e64 s[66:67], v35, v32
	v_cmp_lt_u32_e64 s[68:69], v35, v33
	s_mov_b64 s[80:81], -1
	s_waitcnt vmcnt(0) lgkmcnt(0)
	ds_write_b128 v127, v[48:51]
	ds_write_b128 v127, v[52:55] offset:55296
	ds_write_b128 v127, v[56:59] offset:9216
	ds_write_b128 v127, v[60:63] offset:64512
	s_waitcnt vmcnt(0)
	ds_write_b128 v127, v[64:67] offset:18432
	ds_write_b128 v128, v[68:71]
	ds_write_b128 v127, v[72:75] offset:27648
	ds_write_b128 v129, v[76:79]
	ds_write_b128 v127, v[80:83] offset:36864
	ds_write_b128 v131, v[84:87]
	ds_write_b128 v127, v[88:91] offset:46080
	ds_write_b128 v132, v[92:95]
	s_waitcnt lgkmcnt(0)
	s_barrier
	s_branch .LBB0_605

.LBB0_699:
	s_and_b32 s2, s10, 0x3fffffc0
	s_lshl_b32 s2, s2, 2
	s_add_i32 s17, s2, 0
	s_mul_hi_i32 s2, s8, 0x2aaaaaab
	s_lshr_b32 s6, s2, 31
	s_ashr_i32 s2, s2, 6
	s_add_i32 s17, s17, 0x1c800
	s_and_b32 s3, s38, 31
	s_bfe_u32 s19, s8, 0x20005
	s_add_i32 s2, s2, s6
	s_cmp_eq_u32 s18, 1
	s_cselect_b32 s6, 2, 4
	s_cmp_lg_u32 s18, 0
	s_cselect_b32 s16, s6, 0
	s_lshr_b32 s6, 32, s16
	s_sub_i32 s7, 5, s16
	s_add_i32 s6, s6, -1
	s_lshr_b32 s8, s3, s7
	s_and_b32 s3, s6, s3
	s_lshl_b32 s21, s3, 8
	s_ashr_i32 s3, s2, 31
	s_lshl_b64 s[6:7], s[2:3], 13
	s_lshl_b32 s2, s18, 8
	s_ashr_i32 s3, s2, 31
	s_or_b32 s6, s6, s8
	s_lshl_b64 s[8:9], s[2:3], 1
	s_sub_i32 s2, s21, 64
	v_ashrrev_i32_e32 v1, 3, v0
	s_lshr_b32 s20, 0x2000, s16
	v_add_u32_e32 v2, s2, v1
	v_max_i32_e32 v2, 0, v2
	s_add_i32 s2, s20, -1
	v_min_u32_e32 v2, s2, v2
	v_mov_b32_e32 v3, v233
	v_add_u32_e32 v42, s21, v1
	v_lshlrev_b64 v[2:3], s16, v[2:3]
	v_max_i32_e32 v10, 0, v42
	v_lshl_add_u64 v[2:3], v[2:3], 0, s[6:7]
	v_min_u32_e32 v10, s2, v10
	v_mov_b32_e32 v11, v233
	v_add_u32_e32 v18, 64, v42
	v_readlane_b32 s48, v254, 32
	v_lshlrev_b64 v[2:3], 13, v[2:3]
	v_lshlrev_b64 v[10:11], s16, v[10:11]
	v_max_i32_e32 v18, 0, v18
	v_readlane_b32 s49, v254, 33
	v_lshl_add_u64 v[2:3], s[74:75], 0, v[2:3]
	v_lshl_add_u64 v[10:11], v[10:11], 0, s[6:7]
	v_min_u32_e32 v18, s2, v18
	v_mov_b32_e32 v19, v233
	v_add_u32_e32 v26, 0x80, v42
	s_mov_b32 s13, s49
	s_lshl_b32 s12, s19, 7
	v_lshl_add_u64 v[2:3], v[2:3], 0, s[8:9]
	v_lshlrev_b32_e32 v4, 4, v0
	v_lshlrev_b64 v[10:11], 13, v[10:11]
	v_lshlrev_b64 v[18:19], s16, v[18:19]
	v_max_i32_e32 v26, 0, v26
	v_lshl_add_u64 v[2:3], v[2:3], 0, s[12:13]
	v_cmp_gt_i32_e64 s[30:31], s37, v0
	s_and_saveexec_b64 s[34:35], s[30:31]
	s_bfe_u32 s28, s15, 0x20005
	s_mulk_i32 s28, 0x84
	s_mul_i32 s29, s18, 0x210
	s_add_i32 s29, s29, s28
	v_add_u32_e32 v200, s29, v0
	v_ashrrev_i32_e32 v201, 31, v200
	v_lshl_add_u64 v[200:201], v[200:201], 2, s[4:5]
	global_load_dword v202, v[200:201], off
	s_or_b64 exec, exec, s[34:35]
	v_and_b32_e32 v50, 0x70, v4
	v_mov_b32_e32 v51, v233
	v_lshl_add_u64 v[10:11], s[74:75], 0, v[10:11]
	v_lshl_add_u64 v[18:19], v[18:19], 0, s[6:7]
	v_min_u32_e32 v26, s2, v26
	v_mov_b32_e32 v27, v233
	v_add_u32_e32 v34, 0xc0, v42
	v_lshl_add_u64 v[2:3], v[2:3], 0, v[50:51]
	v_lshl_add_u64 v[10:11], v[10:11], 0, s[8:9]
	v_lshlrev_b64 v[18:19], 13, v[18:19]
	v_lshlrev_b64 v[26:27], s16, v[26:27]
	v_max_i32_e32 v34, 0, v34
	v_add_co_u32_e32 v6, vcc, s36, v2
	v_lshl_add_u64 v[10:11], v[10:11], 0, s[12:13]
	v_lshl_add_u64 v[18:19], s[74:75], 0, v[18:19]
	v_lshl_add_u64 v[26:27], v[26:27], 0, s[6:7]
	v_min_u32_e32 v34, s2, v34
	v_mov_b32_e32 v35, v233
	v_add_u32_e32 v42, 0x100, v42
	v_addc_co_u32_e32 v7, vcc, 0, v3, vcc
	v_lshl_add_u64 v[10:11], v[10:11], 0, v[50:51]
	v_lshl_add_u64 v[18:19], v[18:19], 0, s[8:9]
	v_lshlrev_b64 v[26:27], 13, v[26:27]
	v_lshlrev_b64 v[34:35], s16, v[34:35]
	v_max_i32_e32 v42, 0, v42
	v_add_co_u32_e32 v14, vcc, s36, v10
	v_lshl_add_u64 v[18:19], v[18:19], 0, s[12:13]
	v_lshl_add_u64 v[26:27], s[74:75], 0, v[26:27]
	v_lshl_add_u64 v[34:35], v[34:35], 0, s[6:7]
	v_min_u32_e32 v42, s2, v42
	v_mov_b32_e32 v43, v233
	v_addc_co_u32_e32 v15, vcc, 0, v11, vcc
	v_lshl_add_u64 v[18:19], v[18:19], 0, v[50:51]
	v_lshl_add_u64 v[26:27], v[26:27], 0, s[8:9]
	v_lshlrev_b64 v[34:35], 13, v[34:35]
	v_lshlrev_b64 v[42:43], s16, v[42:43]
	v_add_co_u32_e32 v22, vcc, s36, v18
	v_lshl_add_u64 v[26:27], v[26:27], 0, s[12:13]
	v_lshl_add_u64 v[34:35], s[74:75], 0, v[34:35]
	v_lshl_add_u64 v[42:43], v[42:43], 0, s[6:7]
	s_ashr_i32 s10, s10, 1
	v_addc_co_u32_e32 v23, vcc, 0, v19, vcc
	v_lshl_add_u64 v[26:27], v[26:27], 0, v[50:51]
	v_lshl_add_u64 v[34:35], v[34:35], 0, s[8:9]
	v_lshlrev_b64 v[42:43], 13, v[42:43]
	s_and_b32 s11, s10, 0xffffffe0
	v_add_co_u32_e32 v30, vcc, s36, v26
	v_lshl_add_u64 v[34:35], v[34:35], 0, s[12:13]
	v_lshl_add_u64 v[42:43], s[74:75], 0, v[42:43]
	v_and_b32_e32 v82, 31, v0
	s_add_i32 s22, s11, s21
	v_addc_co_u32_e32 v31, vcc, 0, v27, vcc
	v_lshl_add_u64 v[34:35], v[34:35], 0, v[50:51]
	v_lshl_add_u64 v[42:43], v[42:43], 0, s[8:9]
	v_or_b32_e32 v52, s22, v82
	global_load_dwordx4 v[2:5], v[6:7], off offset:832
	s_nop 0
	global_load_dwordx4 v[6:9], v[6:7], off offset:2368
	s_nop 0
	global_load_dwordx4 v[10:13], v[14:15], off offset:832
	s_nop 0
	global_load_dwordx4 v[14:17], v[14:15], off offset:2368
	v_add_co_u32_e32 v38, vcc, s36, v34
	v_lshl_add_u64 v[42:43], v[42:43], 0, s[12:13]
	v_ashrrev_i32_e32 v53, 31, v52
	global_load_dwordx4 v[18:21], v[22:23], off offset:832
	s_nop 0
	global_load_dwordx4 v[22:25], v[22:23], off offset:2368
	v_addc_co_u32_e32 v39, vcc, 0, v35, vcc
	v_lshl_add_u64 v[42:43], v[42:43], 0, v[50:51]
	v_lshlrev_b64 v[52:53], s16, v[52:53]
	global_load_dwordx4 v[26:29], v[30:31], off offset:832
	s_nop 0
	global_load_dwordx4 v[30:33], v[30:31], off offset:2368
	v_add_co_u32_e32 v46, vcc, s36, v42
	v_lshl_add_u64 v[80:81], v[52:53], 0, s[6:7]
	global_load_dwordx4 v[34:37], v[38:39], off offset:832
	s_nop 0
	global_load_dwordx4 v[38:41], v[38:39], off offset:2368
	v_addc_co_u32_e32 v47, vcc, 0, v43, vcc
	v_lshlrev_b64 v[52:53], 13, v[80:81]
	global_load_dwordx4 v[42:45], v[46:47], off offset:832
	s_nop 0
	global_load_dwordx4 v[46:49], v[46:47], off offset:2368
	v_lshl_add_u64 v[52:53], s[74:75], 0, v[52:53]
	v_bfe_u32 v51, v0, 5, 1
	v_lshl_add_u64 v[52:53], v[52:53], 0, s[8:9]
	v_lshl_add_u64 v[52:53], v[52:53], 0, s[12:13]
	v_lshlrev_b32_e32 v232, 4, v51
	v_lshl_add_u64 v[52:53], v[52:53], 0, v[232:233]
	global_load_dwordx4 v[64:67], v[52:53], off offset:3392
	global_load_dwordx4 v[68:71], v[52:53], off offset:3424
	global_load_dwordx4 v[72:75], v[52:53], off offset:3456
	global_load_dwordx4 v[76:79], v[52:53], off offset:3488
	s_movk_i32 s12, 0x90
	v_mul_lo_u32 v1, v1, s12
	v_add3_u32 v52, 0, v1, v50
	s_add_i32 s3, 0, 0x12000
	s_waitcnt vmcnt(0) lgkmcnt(0)
	s_and_saveexec_b64 s[34:35], s[30:31]
	v_lshl_add_u32 v203, v0, 2, v251
	ds_write_b32 v203, v202
	s_or_b64 exec, exec, s[34:35]
	ds_write_b128 v52, v[2:5]
	ds_write_b128 v52, v[6:9] offset:55296
	ds_write_b128 v52, v[10:13] offset:9216
	ds_write_b128 v52, v[14:17] offset:64512
	ds_write_b128 v52, v[18:21] offset:18432
	v_add3_u32 v2, s3, v1, v50
	ds_write_b128 v2, v[22:25]
	ds_write_b128 v52, v[26:29] offset:27648
	v_add3_u32 v2, s89, v1, v50
	v_readlane_b32 s3, v254, 10
	ds_write_b128 v2, v[30:33]
	ds_write_b128 v52, v[34:37] offset:36864
	v_add3_u32 v2, s3, v1, v50
	ds_write_b128 v2, v[38:41]
	ds_write_b128 v52, v[42:45] offset:46080
	v_readlane_b32 s3, v254, 11
	v_lshlrev_b32_e32 v2, 2, v82
	s_lshl_b32 s10, s10, 2
	v_add3_u32 v1, s3, v1, v50
	v_lshlrev_b32_e32 v83, 2, v51
	v_add_u32_e32 v84, s17, v2
	v_sub_u32_e32 v2, v232, v2
	s_and_b32 s10, s10, 0xffffff80
	ds_write_b128 v1, v[46:49]
	v_lshrrev_b32_e32 v1, 2, v0
	v_subrev_u32_e32 v86, s10, v2
	v_sub_u32_e32 v2, v83, v82
	v_and_or_b32 v1, v1, 3, v83
	v_subrev_u32_e32 v87, s11, v2
	v_lshlrev_b32_e32 v2, 1, v0
	v_and_b32_e32 v0, 3, v0
	s_max_i32 s3, s22, 64
	v_mul_u32_u24_e32 v1, 0x90, v1
	v_and_b32_e32 v2, 32, v2
	v_lshlrev_b32_e32 v0, 3, v0
	v_mov_b32_e32 v14, v233
	v_mov_b32_e32 v15, v233
	s_sub_i32 s25, s3, 64
	s_add_i32 s3, s22, 0x5f
	v_add3_u32 v90, v1, v2, v0
	v_mov_b32_e32 v0, v233
	v_mov_b32_e32 v1, v233
	v_mov_b32_e32 v2, v233
	v_mov_b32_e32 v3, v233
	v_mov_b32_e32 v4, v233
	v_mov_b32_e32 v5, v233
	v_mov_b32_e32 v6, v233
	v_mov_b32_e32 v7, v233
	v_mov_b32_e32 v8, v233
	v_mov_b32_e32 v9, v233
	v_mov_b32_e32 v10, v233
	v_mov_b32_e32 v11, v233
	v_mov_b32_e32 v12, v233
	v_mov_b32_e32 v13, v233
	v_mov_b64_e32 v[30:31], v[14:15]
	s_mov_b32 s41, s49
	s_mov_b32 s24, 0
	s_lshl_b32 s23, s19, 6
	s_min_i32 s26, s3, s2
	v_cmp_eq_u32_e64 s[2:3], 0, v51
	s_sub_i32 s27, 0, s11
	v_lshl_add_u32 v88, v87, 2, v251
	v_or_b32_e32 v89, s21, v83
	v_mad_u32_u24 v91, v82, s12, v232
	v_mov_b32_e32 v85, 0
	v_mov_b32_e32 v92, 0xf149f2ca
	v_mov_b64_e32 v[28:29], v[12:13]
	v_mov_b64_e32 v[26:27], v[10:11]
	v_mov_b64_e32 v[24:25], v[8:9]
	v_mov_b64_e32 v[22:23], v[6:7]
	v_mov_b64_e32 v[20:21], v[4:5]
	v_mov_b64_e32 v[18:19], v[2:3]
	v_mov_b64_e32 v[16:17], v[0:1]
	v_readlane_b32 s50, v254, 34
	v_readlane_b32 s51, v254, 35
	v_readlane_b32 s52, v254, 36
	v_readlane_b32 s53, v254, 37
	v_readlane_b32 s54, v254, 38
	v_readlane_b32 s55, v254, 39
	v_readlane_b32 s56, v254, 40
	v_readlane_b32 s57, v254, 41
	v_readlane_b32 s58, v254, 42
	v_readlane_b32 s59, v254, 43
	v_readlane_b32 s60, v254, 44
	v_readlane_b32 s61, v254, 45
	v_readlane_b32 s62, v254, 46
	v_readlane_b32 s63, v254, 47
	s_waitcnt lgkmcnt(0)
	s_barrier
	s_branch .LBB0_702
